# merge GEMM epilogue: gate loads of each 4-row group issued back to back with one wait instead of load/vmcnt(0) per row
# speedup vs baseline: 1.0396x; 1.0087x over previous
.LBB0_50:
	s_lshl_b32 s6, s6, 8
	s_and_b32 s6, s6, 0x3f00
	v_mov_b32_e32 v132, v221
	v_mov_b32_e32 v133, v222
	s_add_i32 s6, s6, s47
	s_ashr_i32 s8, s49, 2
	v_add_u32_e32 v182, s6, v132
	s_lshl_b32 s6, s49, 8
	s_and_b32 s6, s6, 0x300
	s_or_b32 s6, s6, s48
	v_lshl_add_u32 v180, v133, 3, s6
	s_lshl_b32 s40, s8, 10
	v_mov_b64_e32 v[132:133], s[12:13]
	s_movk_i32 s6, 0x1800
	s_ashr_i32 s41, s40, 31
	v_mad_i64_i32 v[132:133], s[6:7], v182, s6, v[132:133]
	v_ashrrev_i32_e32 v181, 31, v180
	v_lshl_add_u64 v[132:133], s[40:41], 1, v[132:133]
	v_lshl_add_u64 v[184:185], v[180:181], 1, v[132:133]
	global_load_dwordx4 v[160:163], v[184:185], off
	s_cmp_lt_i32 s8, 2
	s_cselect_b64 s[6:7], -1, 0
	s_cmp_gt_i32 s8, 1
	s_cselect_b64 s[42:43], -1, 0
	s_and_b64 vcc, exec, s[42:43]
	s_cbranch_vccnz .LBB0_52
	global_load_dwordx4 v[156:159], v[184:185], off offset:2048
.LBB0_52:
	v_add_u32_e32 v190, 16, v182
	v_mov_b64_e32 v[132:133], s[12:13]
	s_movk_i32 s8, 0x1800
	v_mad_i64_i32 v[132:133], s[8:9], v190, s8, v[132:133]
	v_lshl_add_u64 v[132:133], s[40:41], 1, v[132:133]
	v_lshl_add_u64 v[188:189], v[180:181], 1, v[132:133]
	global_load_dwordx4 v[152:155], v[188:189], off
	v_cndmask_b32_e64 v132, 0, 1, s[6:7]
	v_ashrrev_i32_e32 v183, 31, v182
	v_cmp_ne_u32_e64 s[8:9], 1, v132
	s_andn2_b64 vcc, exec, s[6:7]
	s_cbranch_vccnz .LBB0_54
	global_load_dwordx4 v[148:151], v[188:189], off offset:2048
.LBB0_54:
	v_add_u32_e32 v194, 32, v182
	v_mov_b64_e32 v[132:133], s[12:13]
	s_movk_i32 s6, 0x1800
	v_mad_i64_i32 v[132:133], s[6:7], v194, s6, v[132:133]
	v_lshl_add_u64 v[132:133], s[40:41], 1, v[132:133]
	v_lshl_add_u64 v[192:193], v[180:181], 1, v[132:133]
	global_load_dwordx4 v[144:147], v[192:193], off
	s_and_b64 vcc, exec, s[8:9]
	s_cbranch_vccnz .LBB0_56
	global_load_dwordx4 v[140:143], v[192:193], off offset:2048
.LBB0_56:
	v_add_u32_e32 v198, 48, v182
	v_mov_b64_e32 v[132:133], s[12:13]
	s_movk_i32 s6, 0x1800
	v_mad_i64_i32 v[132:133], s[6:7], v198, s6, v[132:133]
	v_lshl_add_u64 v[132:133], s[40:41], 1, v[132:133]
	v_lshl_add_u64 v[196:197], v[180:181], 1, v[132:133]
	global_load_dwordx4 v[136:139], v[196:197], off
	s_and_b64 vcc, exec, s[8:9]
	s_cbranch_vccnz .LBB0_58
	global_load_dwordx4 v[132:135], v[196:197], off offset:2048
.LBB0_58:
	s_waitcnt vmcnt(0)
	s_and_b64 vcc, exec, s[8:9]
	s_cbranch_vccz .Lmg_skip_0
	v_mov_b64_e32 v[156:157], v[160:161]
	v_mov_b64_e32 v[158:159], v[162:163]
	v_mov_b64_e32 v[148:149], v[152:153]
	v_mov_b64_e32 v[150:151], v[154:155]
	v_mov_b64_e32 v[140:141], v[144:145]
	v_mov_b64_e32 v[142:143], v[146:147]
	v_mov_b64_e32 v[132:133], v[136:137]
	v_mov_b64_e32 v[134:135], v[138:139]

.LBB0_74:
	global_load_dwordx4 v[160:163], v[184:185], off offset:256
	s_and_b64 vcc, exec, s[8:9]
	s_cbranch_vccnz .LBB0_76
	global_load_dwordx4 v[156:159], v[184:185], off offset:2304
.LBB0_76:
	global_load_dwordx4 v[152:155], v[188:189], off offset:256
	s_and_b64 vcc, exec, s[8:9]
	s_cbranch_vccnz .LBB0_78
	global_load_dwordx4 v[148:151], v[188:189], off offset:2304
.LBB0_78:
	global_load_dwordx4 v[144:147], v[192:193], off offset:256
	s_and_b64 vcc, exec, s[8:9]
	s_cbranch_vccnz .LBB0_80
	global_load_dwordx4 v[140:143], v[192:193], off offset:2304
.LBB0_80:
	global_load_dwordx4 v[136:139], v[196:197], off offset:256
	s_and_b64 vcc, exec, s[8:9]
	s_cbranch_vccnz .LBB0_82
	global_load_dwordx4 v[132:135], v[196:197], off offset:2304

.LBB0_98:
	v_add_u32_e32 v198, 0x80, v182
	s_waitcnt vmcnt(0)
	v_mov_b64_e32 v[132:133], s[12:13]
	s_movk_i32 s22, 0x1800
	v_mad_i64_i32 v[132:133], s[22:23], v198, s22, v[132:133]
	v_lshl_add_u64 v[132:133], s[40:41], 1, v[132:133]
	v_lshl_add_u64 v[184:185], v[180:181], 1, v[132:133]
	global_load_dwordx4 v[160:163], v[184:185], off
	s_and_b64 vcc, exec, s[8:9]
	s_cbranch_vccnz .LBB0_100
	global_load_dwordx4 v[156:159], v[184:185], off offset:2048
.LBB0_100:
	v_add_u32_e32 v188, 0x90, v182
	v_mov_b64_e32 v[132:133], s[12:13]
	s_movk_i32 s22, 0x1800
	v_mad_i64_i32 v[132:133], s[22:23], v188, s22, v[132:133]
	v_lshl_add_u64 v[132:133], s[40:41], 1, v[132:133]
	v_lshl_add_u64 v[186:187], v[180:181], 1, v[132:133]
	global_load_dwordx4 v[152:155], v[186:187], off
	s_and_b64 vcc, exec, s[8:9]
	s_cbranch_vccnz .LBB0_102
	global_load_dwordx4 v[148:151], v[186:187], off offset:2048
.LBB0_102:
	v_add_u32_e32 v190, 0xa0, v182
	v_mov_b64_e32 v[132:133], s[12:13]
	s_movk_i32 s22, 0x1800
	v_mad_i64_i32 v[132:133], s[22:23], v190, s22, v[132:133]
	v_lshl_add_u64 v[132:133], s[40:41], 1, v[132:133]
	v_lshl_add_u64 v[192:193], v[180:181], 1, v[132:133]
	global_load_dwordx4 v[144:147], v[192:193], off
	s_and_b64 vcc, exec, s[8:9]
	s_cbranch_vccnz .LBB0_104
	global_load_dwordx4 v[140:143], v[192:193], off offset:2048
.LBB0_104:
	v_add_u32_e32 v194, 0xb0, v182
	v_mov_b64_e32 v[132:133], s[12:13]
	s_movk_i32 s22, 0x1800
	v_mad_i64_i32 v[132:133], s[22:23], v194, s22, v[132:133]
	v_lshl_add_u64 v[132:133], s[40:41], 1, v[132:133]
	v_lshl_add_u64 v[196:197], v[180:181], 1, v[132:133]
	global_load_dwordx4 v[136:139], v[196:197], off
	s_and_b64 vcc, exec, s[8:9]
	s_cbranch_vccnz .LBB0_106
	global_load_dwordx4 v[132:135], v[196:197], off offset:2048

.LBB0_124:
	global_load_dwordx4 v[152:155], v[186:187], off offset:256
	s_and_b64 vcc, exec, s[8:9]
	s_cbranch_vccnz .LBB0_126
	global_load_dwordx4 v[148:151], v[186:187], off offset:2304
